# weight conversion for later layers moved from the prep phase into the idle half (blockIdx>=128) of each FFN-up phase tail; prep converts only layer-0 matrices
# speedup vs baseline: 1.0358x; 1.0358x over previous
; #define LAS __attribute__((address_space(3)))
; __device__ __forceinline__ int opaque_tid() { int t = threadIdx.x; asm volatile("" : "+v"(t)); return t; }
; __device__ __forceinline__ void convert_weights(const Args& a, float* ldsf, unsigned mask, int wb, int nwb) {
;     const int tid = opaque_tid(), lane = tid & 63, wave = tid >> 6;
;     const int gw = wb * NWAVES + wave, NGW = nwb * NWAVES;
; __global__ void __launch_bounds__(NTHREADS, 2) mk_fwd(Args a) {
;     extern __shared__ __attribute__((aligned(16))) unsigned char lds[];
;     unsigned char* ws = a.ws;
;     bf16_t* XB = (bf16_t*)(ws + WS_XB); bf16_t* BIG = (bf16_t*)(ws + WS_BIG); float* RSX = (float*)(ws + WS_RSX); float* SSQP = (float*)(ws + WS_SSQP);
;     volatile LAS unsigned* bst = (volatile LAS unsigned*)((LAS unsigned char*)lds + 131072);
;     if (threadIdx.x == 0) { bst[0] = 0u; bst[1] = 0u; }
;     __syncthreads();
;     (void)xcd_barrier_post((unsigned*)(ws + WS_BAR), bst);
;     const bool fusedres = (FUSE_RESID != 0) && (gridDim.x == 256) && (a.ph_hi - a.ph_lo > 1);
.LBB0_6:
	s_load_dword s27, s[0:1], 0xb8
	s_add_u32 s2, s0, 0xb8
	s_addc_u32 s3, s1, 0
	v_writelane_b32 v253, s2, 12
	s_load_dwordx16 s[36:51], s[0:1], 0x0
	s_waitcnt lgkmcnt(0)
	s_lshl_b32 s101, s27, 3
	s_mov_b32 s100, 0xffff
	s_cmp_lg_u32 s27, 0x100
	s_cbranch_scc1 .Lcv_init_done
	s_mov_b32 s100, 0x10d
.Lcv_init_done:
	s_cmpk_eq_i32 s27, 0x100
	v_writelane_b32 v253, s3, 13
	s_cselect_b64 s[2:3], -1, 0
	s_sub_i32 s4, s35, s34
	s_cmp_gt_i32 s4, 1
	s_cselect_b64 s[4:5], -1, 0
	s_and_b64 s[2:3], s[2:3], s[4:5]
	s_xor_b64 s[94:95], s[2:3], -1
	s_add_u32 s2, s30, 0x7300000
	s_addc_u32 s3, s31, 0
	v_writelane_b32 v253, s2, 14
	s_load_dwordx16 s[52:67], s[0:1], 0x40
	v_mbcnt_lo_u32_b32 v1, -1, 0
	v_writelane_b32 v253, s3, 15
	s_add_u32 s2, s30, 0x9300000
	s_addc_u32 s3, s31, 0
	v_writelane_b32 v253, s2, 16
	v_mbcnt_hi_u32_b32 v207, -1, v1
	v_mov_b32_e32 v3, 0
	v_writelane_b32 v253, s3, 17
	s_add_u32 s2, s30, 0x15d40000
	s_addc_u32 s3, s31, 0
	v_writelane_b32 v253, s2, 18
	v_and_b32_e32 v1, 64, v207
	v_mov_b32_e32 v252, 0x2000
	v_writelane_b32 v253, s3, 19
	s_add_u32 s2, s30, 0x15d80000
	s_addc_u32 s3, s31, 0
	s_add_u32 s96, s30, 0x15ec0200
	s_addc_u32 s97, s31, 0
	s_add_u32 s80, s30, 0x15ec0400
	s_addc_u32 s81, s31, 0
	s_add_u32 s88, s30, 0x15ec0500
	v_writelane_b32 v253, s2, 20
	s_addc_u32 s89, s31, 0
	v_mov_b32_e32 v171, 1
	v_writelane_b32 v253, s3, 21
	s_add_u32 s2, s30, 0x15ec0600
	s_addc_u32 s3, s31, 0
	v_writelane_b32 v253, s2, 22
	v_mov_b32_e32 v170, 0x358637bd
	v_mov_b32_e32 v206, 0x3ecc95a3
	v_writelane_b32 v253, s3, 23
	s_add_u32 s2, s30, 0x15ec0700
	s_addc_u32 s3, s31, 0
	v_writelane_b32 v253, s2, 24
	v_add_u32_e32 v208, 64, v1
	v_xor_b32_e32 v209, 1, v207
	v_writelane_b32 v253, s3, 25
	s_add_u32 s2, s30, 0x15ec0800
	s_addc_u32 s3, s31, 0
	v_writelane_b32 v253, s2, 26
	v_xor_b32_e32 v210, 2, v207
	v_xor_b32_e32 v211, 4, v207
	v_writelane_b32 v253, s3, 27
	s_add_u32 s2, s30, 0x15ec0900
	s_addc_u32 s3, s31, 0
	v_writelane_b32 v253, s2, 28
	v_xor_b32_e32 v212, 8, v207
	v_xor_b32_e32 v213, 16, v207
	v_writelane_b32 v253, s3, 29
	s_add_u32 s2, s30, 0x15ec0a00
	s_addc_u32 s3, s31, 0
	v_writelane_b32 v253, s2, 30
	v_xor_b32_e32 v214, 32, v207
	v_mov_b32_e32 v215, 0x3fb8aa3b
	v_writelane_b32 v253, s3, 31
	s_add_u32 s2, s30, 0x15ec0b00
	s_addc_u32 s3, s31, 0
	v_writelane_b32 v253, s2, 32
	v_mov_b32_e32 v174, 0x3f317218
	v_mov_b32_e32 v216, 0x7f800000
	v_writelane_b32 v253, s3, 33
	s_add_u32 s2, s30, 0x15ec0c00
	s_addc_u32 s3, s31, 0
	v_writelane_b32 v253, s2, 34
	v_mov_b32_e32 v217, 0x7fc00000
	v_mov_b32_e32 v218, 0xff800000
	v_writelane_b32 v253, s3, 35
	s_add_u32 s2, s30, 0x15ec0d00
	s_addc_u32 s3, s31, 0
	v_writelane_b32 v253, s2, 36
	v_mov_b32_e32 v219, 0x1600
	v_mov_b32_e32 v6, v3
	v_writelane_b32 v253, s3, 37
	s_add_u32 s2, s30, 0x15ec0e00
	s_addc_u32 s3, s31, 0
	v_writelane_b32 v253, s2, 38
	v_mov_b32_e32 v7, v3
	v_mov_b32_e32 v8, v3
	v_writelane_b32 v253, s3, 39
	s_add_u32 s2, s30, 0x15ec0f00
	s_addc_u32 s3, s31, 0
	v_writelane_b32 v253, s2, 40
	v_mov_b32_e32 v9, v3
	v_mov_b32_e32 v242, v3
	v_writelane_b32 v253, s3, 41
	s_add_u32 s2, s30, 0x15ec1000
	s_addc_u32 s3, s31, 0
	v_writelane_b32 v253, s2, 42
	v_mov_b32_e32 v243, v3
	s_mov_b32 s18, 0x9301000
	v_writelane_b32 v253, s3, 43
	s_add_u32 s2, s30, 0x15ec1100
	s_addc_u32 s3, s31, 0
	v_writelane_b32 v253, s2, 44
	s_mov_b32 s26, 0x9300000
	s_mov_b32 s33, 0xc0000
	v_writelane_b32 v253, s3, 45
	s_add_u32 s2, s30, 0x15ec1200
	s_addc_u32 s3, s31, 0
	v_writelane_b32 v253, s2, 46
	s_movk_i32 s79, 0x84
	s_mov_b64 s[70:71], 0x80
	v_writelane_b32 v253, s3, 47
	s_add_u32 s2, s30, 0x15ec1300
	s_addc_u32 s3, s31, 0
	v_writelane_b32 v253, s2, 48
	s_nop 1
	v_writelane_b32 v253, s3, 49
	s_add_u32 s2, s30, 0x15ec3400
	s_addc_u32 s3, s31, 0
	v_writelane_b32 v253, s2, 50
	s_nop 1
	v_writelane_b32 v253, s3, 51
	s_add_u32 s2, s30, 0x15ec3500
	s_addc_u32 s3, s31, 0
	v_writelane_b32 v253, s2, 52
	s_nop 1
	v_writelane_b32 v253, s3, 53
	s_add_u32 s2, s30, 0x3100000
	v_writelane_b32 v253, s2, 54
	s_addc_u32 s2, s31, 0
	v_writelane_b32 v253, s2, 55
	s_add_u32 s2, s30, 0x2100000
	v_writelane_b32 v253, s2, 56
; #define LAS __attribute__((address_space(3)))
; __device__ __forceinline__ unsigned xb_xcc_id() { return (unsigned)__builtin_amdgcn_s_getreg((3 << 11) | 20) & 0xFu; }
; __host__ __device__ inline bool phase_exists(int ph) { if (ph == 0) return true; const int li = (ph - 1) / 9, s = (ph - 1) % 9; return !((li & 1) && s == 2) && s != 6; }
; __global__ void __launch_bounds__(NTHREADS, 2) mk_fwd(Args a) {
;     extern __shared__ __attribute__((aligned(16))) unsigned char lds[];
;     unsigned char* ws = a.ws;
;     bf16_t* XB = (bf16_t*)(ws + WS_XB); bf16_t* BIG = (bf16_t*)(ws + WS_BIG); float* RSX = (float*)(ws + WS_RSX); float* SSQP = (float*)(ws + WS_SSQP);
;     volatile LAS unsigned* bst = (volatile LAS unsigned*)((LAS unsigned char*)lds + 131072);
;     if (threadIdx.x == 0) { bst[0] = 0u; bst[1] = 0u; }
;     __syncthreads();
;     (void)xcd_barrier_post((unsigned*)(ws + WS_BAR), bst);
;     const bool fusedres = (FUSE_RESID != 0) && (gridDim.x == 256) && (a.ph_hi - a.ph_lo > 1);
;     bool first = true;
;     for (int ph = a.ph_lo; ph < a.ph_hi; ++ph) {
;         if (!phase_exists(ph)) continue;
;         if (fusedres && ph > 0 && ((ph - 1) % 9 == 4 || (ph - 1) % 9 == 8)) continue;
;         if (!first) { XcdBarrier xbar; xbar.bar = (unsigned*)(ws + WS_BAR); xbar.x = xb_xcc_id(); xbar.st = bst; xcd_barrier(xbar); if (PROBE == 2) xcd_barrier(xbar); }
;         first = false;
;         if (ph == 0) { phase_prep(a, (float*)lds); continue; }
;         const int li = (ph - 1) / 9, s = (ph - 1) % 9, j = li >> 1; const bool ssd = !(li & 1);
	s_addc_u32 s2, s31, 0
	v_writelane_b32 v253, s2, 57
	s_lshl_b32 s2, s92, 3
	s_lshl_b32 s76, s27, 3
	v_writelane_b32 v253, s2, 58
	s_add_u32 s2, s30, 0xeb00000
	s_addc_u32 s3, s31, 0
	v_writelane_b32 v253, s2, 59
	s_nop 1
	v_writelane_b32 v253, s3, 60
	s_add_u32 s2, s30, 0x15300000
	s_addc_u32 s3, s31, 0
	v_writelane_b32 v253, s2, 61
	s_cmpk_lt_i32 s92, 0x100
	s_nop 0
	v_writelane_b32 v253, s3, 62
	s_cselect_b64 s[2:3], -1, 0
	v_writelane_b32 v253, s2, 63
	s_nop 1
	v_writelane_b32 v254, s3, 0
	s_add_u32 s2, s30, 0x15500000
	s_addc_u32 s3, s31, 0
	v_writelane_b32 v254, s2, 1
	s_lshl_b32 s90, s27, 9
	s_nop 0
	v_writelane_b32 v254, s3, 2
	s_lshl_b32 s2, s92, 9
	v_writelane_b32 v254, s2, 3
	s_and_b32 s2, s27, 0x1fffffff
	s_cmpk_lg_i32 s2, 0x100
	s_cselect_b64 s[2:3], -1, 0
	v_writelane_b32 v254, s2, 4
	s_nop 1
	v_writelane_b32 v254, s3, 5
	s_add_u32 s2, s30, 0x5d00000
	v_writelane_b32 v254, s2, 6
	s_addc_u32 s2, s31, 0
	v_writelane_b32 v254, s2, 7
	s_add_u32 s2, s30, 0x2d00000
	v_writelane_b32 v254, s2, 8
	s_addc_u32 s2, s31, 0
	v_writelane_b32 v254, s2, 9
	s_add_u32 s2, s30, 0x9300800
	s_addc_u32 s3, s31, 0
	v_writelane_b32 v254, s2, 10
	s_add_u32 s78, s30, 0x1900000
	s_nop 0
	v_writelane_b32 v254, s3, 11
	s_addc_u32 s2, s31, 0
	v_writelane_b32 v254, s2, 12
	s_add_u32 s2, s30, 0x9301000
	s_addc_u32 s3, s31, 0
	v_writelane_b32 v254, s2, 13
	s_nop 1
	v_writelane_b32 v254, s3, 14
	s_add_u32 s2, s30, 0x15a80000
	s_addc_u32 s3, s31, 0
	v_writelane_b32 v254, s2, 15
	s_ashr_i32 s93, s92, 31
	s_nop 0
	v_writelane_b32 v254, s3, 16
	s_lshr_b32 s2, s93, 29
	s_add_i32 s2, s92, s2
	s_ashr_i32 s3, s2, 3
	s_and_b32 s2, s2, -8
	v_writelane_b32 v254, s3, 17
	s_sub_i32 s2, s92, s2
	s_ashr_i32 s3, s27, 31
	v_writelane_b32 v254, s3, 18
	s_add_u32 s3, s30, 0x15ec8000
	v_writelane_b32 v254, s3, 19
	s_addc_u32 s3, s31, 0
	v_writelane_b32 v254, s3, 20
	s_add_u32 s3, s30, 0x15ec4000
	v_writelane_b32 v254, s3, 21
	s_addc_u32 s3, s31, 0
	s_cmp_lt_i32 s2, 0
	v_writelane_b32 v254, s3, 22
	s_cselect_b64 s[4:5], -1, 0
	v_writelane_b32 v254, s4, 23
	s_ashr_i32 s77, s76, 31
	s_nop 0
	v_writelane_b32 v254, s5, 24
	v_writelane_b32 v254, s2, 25
	s_lshr_b32 s2, s2, 31
	v_writelane_b32 v254, s2, 26
	s_lshl_b64 s[2:3], s[76:77], 11
	v_writelane_b32 v254, s2, 27
	s_mov_b64 s[4:5], -1
	s_nop 0
	v_writelane_b32 v254, s3, 28
	s_lshl_b64 s[2:3], s[76:77], 6
	v_writelane_b32 v254, s2, 29
	s_nop 1
	v_writelane_b32 v254, s3, 30
	s_lshl_b64 s[2:3], s[76:77], 4
	v_writelane_b32 v254, s2, 31
	s_nop 1
	v_writelane_b32 v254, s3, 32
	s_add_u32 s2, s28, 0x800
	s_addc_u32 s3, s29, 0
	v_writelane_b32 v254, s2, 33
	s_nop 1
	v_writelane_b32 v254, s3, 34
	s_lshl_b32 s2, s92, 12
	v_writelane_b32 v254, s2, 35
	s_lshl_b32 s2, s27, 12
	v_writelane_b32 v254, s2, 36
	s_lshl_b32 s2, s92, 7
	v_writelane_b32 v254, s2, 37
	s_lshl_b32 s2, s27, 7
	v_writelane_b32 v254, s2, 38
	s_lshl_b64 s[2:3], s[76:77], 12
	v_writelane_b32 v254, s2, 39
	s_nop 1
	v_writelane_b32 v254, s3, 40
	s_lshl_b64 s[2:3], s[76:77], 1
	v_writelane_b32 v254, s2, 41
	s_movk_i32 s77, 0x80
	s_nop 0
	v_writelane_b32 v254, s3, 42
	s_add_u32 s2, s30, 0x15e80000
	s_addc_u32 s3, s31, 0
	v_writelane_b32 v254, s2, 43
	s_ashr_i32 s91, s90, 31
	s_nop 0
	v_writelane_b32 v254, s3, 44
	s_lshl_b64 s[2:3], s[90:91], 3
	v_writelane_b32 v254, s2, 45
	s_nop 1
	v_writelane_b32 v254, s3, 46
	s_add_u32 s2, s36, 0x800
	s_addc_u32 s3, s37, 0
	v_writelane_b32 v254, s2, 47
	s_add_i32 s91, 0, 0x10000
	s_mov_b32 s37, 0
	v_writelane_b32 v254, s3, 48
	s_add_i32 s2, 0, 0x20000
	v_writelane_b32 v254, s2, 49
	s_add_i32 s2, 0, 0x20004
	v_writelane_b32 v254, s2, 50
	s_add_i32 s2, 0, 0x12400
	v_writelane_b32 v254, s2, 51
	s_add_i32 s2, 0, 0x14600
	v_writelane_b32 v254, s2, 52
	v_writelane_b32 v254, s92, 53
	s_nop 1
	v_writelane_b32 v254, s93, 54
	v_writelane_b32 v254, s80, 55
	s_nop 1
	v_writelane_b32 v254, s81, 56
	v_writelane_b32 v254, s88, 57
	s_nop 1
	v_writelane_b32 v254, s89, 58
	v_writelane_b32 v254, s78, 59
	v_writelane_b32 v254, s94, 60
	s_nop 1
	v_writelane_b32 v254, s95, 61
	v_writelane_b32 v254, s96, 62
	s_nop 1
	v_writelane_b32 v254, s97, 63
	s_branch .LBB0_10

; __global__ void __launch_bounds__(NTHREADS, 2) mk_fwd(Args a) {
;     ...
;             if (rep == 0) {
;                 unsigned cmask = 0u;
;                 if (s == 0 && li == 0) cmask = (1u << 2) | (1u << 8) | (1u << 12);
;                 else if (s == 5 && li == 0) cmask = (1u << 4) | (1u << 6) | (1u << 9) | (1u << 13);
;                 else if (s == 5 && li == 1) cmask = (1u << 1) | (1u << 3) | (1u << 10) | (1u << 14);
;                 else if (s == 0 && li == 2) cmask = (1u << 5) | (1u << 7) | (1u << 11) | (1u << 15);
;                 if (cmask) {
;                     const int G = (int)gridDim.x, rem = S.nwg % G;
;                     if (rem == 0) convert_weights(a, (float*)lds, cmask, (int)blockIdx.x, G);
;                     else if ((int)blockIdx.x >= rem) convert_weights(a, (float*)lds, cmask, (int)blockIdx.x - rem, G - rem);
;                 }
;             }
.LBB0_281:
	s_waitcnt vmcnt(0)
	v_readlane_b32 s92, v254, 53
	v_readlane_b32 s80, v254, 55
	v_readlane_b32 s88, v254, 57
	v_readlane_b32 s93, v254, 54
	v_readlane_b32 s81, v254, 56
	v_readlane_b32 s89, v254, 58
	s_mov_b32 s26, 0x9300000
	v_readlane_b32 s73, v255, 28
	s_barrier
	s_cmp_lg_u32 s27, 0x100
	s_cbranch_scc1 .LBB0_282
	s_cmp_lt_u32 s92, 0x80
	s_cbranch_scc1 .LBB0_282
	s_mov_b32 s100, 0x11250
	s_cmp_eq_u32 s34, 15
	s_cbranch_scc0 .Lcv_m1
	s_mov_b32 s100, 0x12402
.Lcv_m1:
	s_cmp_eq_u32 s34, 24
	s_cbranch_scc0 .Lcv_m2
	s_mov_b32 s100, 0x148a0
.Lcv_m2:
	s_cmp_eq_u32 s34, 33
	s_cbranch_scc0 .Lcv_m3
	s_mov_b32 s100, 0x18000
.Lcv_m3:
	s_mov_b32 s101, 0x400
	s_branch .LBB0_482
.Lcv_tail_ret:
	s_mov_b32 s100, 0

; __device__ __forceinline__ int opaque_tid() { int t = threadIdx.x; asm volatile("" : "+v"(t)); return t; }
; __device__ __forceinline__ void convert_weights(const Args& a, float* ldsf, unsigned mask, int wb, int nwb) {
;     const int tid = opaque_tid(), lane = tid & 63, wave = tid >> 6;
;     const int gw = wb * NWAVES + wave, NGW = nwb * NWAVES;
;     float* scr = ldsf + wave * 2304;
;     unsigned char* ws = a.ws;
.LBB0_482:
	v_mov_b32_e32 v13, v0
	v_mov_b32_e32 v1, v0
	v_readlane_b32 s0, v253, 58
	s_bitcmp1_b32 s100, 16
	s_cbranch_scc0 .Lcv_a
	s_addk_i32 s0, 0xfc00
.Lcv_a:
	s_waitcnt vmcnt(0) lgkmcnt(0)
	v_ashrrev_i32_e32 v2, 6, v1
	v_and_b32_e32 v14, 7, v1
	s_waitcnt lgkmcnt(0)
	v_add_u32_e32 v11, s0, v2
	s_movk_i32 s0, 0x2400
	v_mul_lo_u32 v2, v2, s0
	v_bfe_u32 v23, v1, 3, 3
	v_add_u32_e32 v5, 0, v2
	v_bfe_u32 v4, v1, 5, 1
	v_and_b32_e32 v2, 31, v1
	v_lshlrev_b32_e32 v12, 3, v14
	v_mul_u32_u24_e32 v1, 0x420, v14
	v_lshlrev_b32_e32 v14, 2, v23
	v_lshl_add_u32 v10, v2, 2, v5
	v_add3_u32 v52, v5, v1, v14
	v_or_b32_e32 v53, 8, v23
	v_or_b32_e32 v54, 16, v23
	v_or_b32_e32 v55, 24, v23
	v_mov_b32_e32 v1, v4
	s_mov_b32 s2, 0
	v_lshlrev_b32_e32 v2, 2, v2
	s_branch .LBB0_484

; __device__ __forceinline__ void convert_weights(const Args& a, float* ldsf, unsigned mask, int wb, int nwb) {
;     ...
;     for (int mi = 0; mi < 16; ++mi) {
;         if (!((mask >> mi) & 1u)) continue;
;         const float* W; bf16_t* WT; const float* ks; int K, N;
;         if (mi < 2) { const int j = mi; W = a.in[5] + (size_t)j * 1024 * SSD_IN_N; K = 1024; N = SSD_IN_N; WT = (bf16_t*)(ws + WS_SSDIN + j * SZ_SSDIN1); ks = a.in[1] + (2 * j) * 1024; }
;         else if (mi < 4) { const int j = mi - 2; W = a.in[12] + (size_t)j * 2048 * 1024; K = 2048; N = 1024; WT = (bf16_t*)(ws + WS_SSDOUT + j * SZ_SSDOUT1); ks = a.in[11] + j * 2048; }
;         else if (mi < 6) { const int j = mi - 4; W = a.in[13] + (size_t)j * 1024 * 3072; K = 1024; N = 3072; WT = (bf16_t*)(ws + WS_SCIN + j * SZ_SCIN1); ks = a.in[1] + (2 * j + 1) * 1024; }
;         else if (mi < 8) { const int j = mi - 6; W = a.in[15] + (size_t)j * 1024 * 1024; K = 1024; N = 1024; WT = (bf16_t*)(ws + WS_SCOUT + j * SZ_SCOUT1); ks = nullptr; }
;         else if (mi < 12) { const int i = mi - 8; W = a.in[16] + (size_t)i * 1024 * FH2; K = 1024; N = FH2; WT = (bf16_t*)(ws + WS_FUP + i * SZ_FUP1); ks = a.in[3] + i * 1024; }
;         else { const int i = mi - 12; W = a.in[19] + (size_t)i * FH * 1024; K = FH; N = 1024; WT = (bf16_t*)(ws + WS_FDN + i * SZ_FDN1); ks = nullptr; }
.Lcv_next:
	s_add_i32 s2, s2, 1
	v_readlane_b32 s6, v254, 45
	s_cmp_lg_u32 s2, 16
	v_readlane_b32 s7, v254, 46
	s_mov_b32 s18, 0x9301000
	s_cbranch_scc0 .LBB0_542
.LBB0_484:
	s_bitcmp1_b32 s100, s2
	s_cbranch_scc0 .Lcv_next
	s_cmp_gt_u32 s2, 1
	s_mov_b64 s[6:7], -1
	s_cbranch_scc0 .LBB0_501
	s_cmp_gt_u32 s2, 3
	s_cbranch_scc0 .LBB0_498
	s_cmp_gt_u32 s2, 5
	s_cbranch_scc0 .LBB0_495
	s_cmp_gt_u32 s2, 7
	s_cbranch_scc0 .LBB0_492
	s_cmp_gt_u32 s2, 11
	s_mov_b64 s[4:5], -1
	s_cbranch_scc0 .LBB0_490
	s_add_i32 s3, s2, -12
	v_readlane_b32 s4, v253, 0
	s_mul_i32 s0, s3, 0xb00000
	v_readlane_b32 s10, v253, 6
	s_mul_hi_u32 s1, s3, 0xb00000
	v_readlane_b32 s5, v253, 1
	v_readlane_b32 s11, v253, 7
	s_add_u32 s0, s10, s0
	s_addc_u32 s1, s11, s1
	s_mul_hi_u32 s4, s3, 0x580000
	s_mul_i32 s3, s3, 0x580000
	v_readlane_b32 s5, v254, 6
	s_add_u32 s12, s5, s3
	v_readlane_b32 s3, v254, 7
	v_readlane_b32 s6, v253, 2
	v_readlane_b32 s7, v253, 3
	v_readlane_b32 s8, v253, 4
	v_readlane_b32 s9, v253, 5
	s_addc_u32 s13, s3, s4
	s_mov_b64 s[4:5], 0

; __device__ __forceinline__ unsigned pk2(float lo, float hi) { unsigned r; asm volatile("v_cvt_pk_bf16_f32 %0, %1, %2" : "=v"(r) : "v"(lo), "v"(hi)); return r; }
; __device__ __forceinline__ void p0_transpose_item(const float* W, int K, int N, bf16_t* WT, const float* ks, float* scr, int item, int lane, int ilv) {
;     ...
;     const int c = lane & 7;
;     float sc[8];
; #pragma unroll
;     for (int q = 0; q < 8; ++q) sc[q] = ks ? ks[k0 + 8 * c + q] : 1.0f;
; #pragma unroll
;     for (int jj = 0; jj < 4; ++jj) { const int n = (lane >> 3) + 8 * jj; const float* s = scr + (8 * c) * 33 + n;
;         uint4 o; o.x = pk2(s[0 * 33] * sc[0], s[1 * 33] * sc[1]); o.y = pk2(s[2 * 33] * sc[2], s[3 * 33] * sc[3]); o.z = pk2(s[4 * 33] * sc[4], s[5 * 33] * sc[5]); o.w = pk2(s[6 * 33] * sc[6], s[7 * 33] * sc[7]);
;         *(uint4*)(WT + (size_t)(d0 + n) * K + k0 + 8 * c) = o; }
; __device__ __forceinline__ void convert_weights(const Args& a, float* ldsf, unsigned mask, int wb, int nwb) {
;     ...
;         for (int it = gw; it < nitems; it += NGW) p0_transpose_item(W, K, N, WT, ks, scr, it, lane, (mi >= 8 && mi < 12) ? 1 : ((mi >= 4 && mi < 6) ? 2 : 0));
.LBB0_505:
	ds_read2_b32 v[20:21], v52 offset1:33
	v_add_u32_e32 v33, v58, v23
	v_ashrrev_i32_e32 v37, 31, v33
	v_add_u32_e32 v57, s101, v57
	v_cmp_le_i32_e32 vcc, s16, v57
	s_waitcnt vmcnt(0) lgkmcnt(0)
	v_mul_f32_e32 v19, v22, v20
	v_mul_f32_e32 v20, v5, v21
	v_cvt_pk_bf16_f32 v30, v19, v20
	ds_read2_b32 v[20:21], v52 offset0:66 offset1:99
	s_or_b64 s[8:9], vcc, s[8:9]
	s_waitcnt lgkmcnt(0)
	v_mul_f32_e32 v19, v25, v20
	v_mul_f32_e32 v20, v24, v21
	v_cvt_pk_bf16_f32 v31, v19, v20
	ds_read2_b32 v[20:21], v52 offset0:132 offset1:165
	v_ashrrev_i32_e32 v19, 31, v18
	v_lshl_add_u64 v[34:35], v[18:19], 1, v[16:17]
	s_waitcnt lgkmcnt(0)
	v_mul_f32_e32 v18, v27, v20
	v_mul_f32_e32 v19, v26, v21
	v_cvt_pk_bf16_f32 v32, v18, v19
	ds_read2_b32 v[18:19], v52 offset0:198 offset1:231
	v_mad_u64_u32 v[20:21], s[0:1], v33, s3, 0
	v_mov_b32_e32 v36, v21
	v_mad_u64_u32 v[36:37], s[0:1], v37, s3, v[36:37]
	s_waitcnt lgkmcnt(0)
	v_mul_f32_e32 v18, v29, v18
	v_mul_f32_e32 v19, v28, v19
	v_cvt_pk_bf16_f32 v33, v18, v19
	ds_read2_b32 v[18:19], v52 offset0:8 offset1:41
	v_mov_b32_e32 v21, v36
	v_lshl_add_u64 v[20:21], v[20:21], 1, v[34:35]
	global_store_dwordx4 v[20:21], v[30:33], off
	s_waitcnt lgkmcnt(0)
	v_mul_f32_e32 v18, v22, v18
	v_mul_f32_e32 v19, v5, v19
	v_cvt_pk_bf16_f32 v18, v18, v19
	ds_read2_b32 v[20:21], v52 offset0:74 offset1:107
	v_add_u32_e32 v32, v58, v53
	v_ashrrev_i32_e32 v37, 31, v32
	v_mad_u64_u32 v[32:33], s[0:1], v32, s3, 0
	s_waitcnt lgkmcnt(0)
	v_mul_f32_e32 v19, v25, v20
	v_mul_f32_e32 v20, v24, v21
	v_cvt_pk_bf16_f32 v19, v19, v20
	ds_read2_b32 v[20:21], v52 offset0:140 offset1:173
	v_mov_b32_e32 v36, v33
	v_mad_u64_u32 v[36:37], s[0:1], v37, s3, v[36:37]
	v_mov_b32_e32 v33, v36
	s_waitcnt lgkmcnt(0)
	v_mul_f32_e32 v20, v27, v20
	v_mul_f32_e32 v21, v26, v21
	v_cvt_pk_bf16_f32 v20, v20, v21
	ds_read2_b32 v[30:31], v52 offset0:206 offset1:239
	v_lshl_add_u64 v[32:33], v[32:33], 1, v[34:35]
	s_waitcnt lgkmcnt(0)
	v_mul_f32_e32 v21, v29, v30
	v_mul_f32_e32 v30, v28, v31
	v_cvt_pk_bf16_f32 v21, v21, v30
	ds_read2_b32 v[30:31], v52 offset0:16 offset1:49
	global_store_dwordx4 v[32:33], v[18:21], off
	v_add_u32_e32 v32, v58, v54
	v_ashrrev_i32_e32 v33, 31, v32
	s_waitcnt lgkmcnt(0)
	v_mul_f32_e32 v18, v22, v30
	v_mul_f32_e32 v19, v5, v31
	v_cvt_pk_bf16_f32 v18, v18, v19
	ds_read2_b32 v[20:21], v52 offset0:82 offset1:115
	s_waitcnt lgkmcnt(0)
	v_mul_f32_e32 v19, v25, v20
	v_mul_f32_e32 v20, v24, v21
	v_cvt_pk_bf16_f32 v19, v19, v20
	ds_read2_b32 v[20:21], v52 offset0:148 offset1:181
	s_waitcnt lgkmcnt(0)
	v_mul_f32_e32 v20, v27, v20
	v_mul_f32_e32 v21, v26, v21
	v_cvt_pk_bf16_f32 v20, v20, v21
	ds_read2_b32 v[30:31], v52 offset0:214 offset1:247
	s_waitcnt lgkmcnt(0)
	v_mul_f32_e32 v21, v29, v30
	v_mul_f32_e32 v30, v28, v31
	v_cvt_pk_bf16_f32 v21, v21, v30
	v_mad_u64_u32 v[30:31], s[0:1], v32, s3, 0
	ds_read2_b32 v[36:37], v52 offset0:24 offset1:57
	v_mov_b32_e32 v32, v31
	v_mad_u64_u32 v[32:33], s[0:1], v33, s3, v[32:33]
	v_mov_b32_e32 v31, v32
	v_lshl_add_u64 v[30:31], v[30:31], 1, v[34:35]
	global_store_dwordx4 v[30:31], v[18:21], off
	s_waitcnt lgkmcnt(0)
	v_mul_f32_e32 v5, v5, v37
	v_mul_f32_e32 v18, v22, v36
	v_cvt_pk_bf16_f32 v18, v18, v5
	ds_read2_b32 v[20:21], v52 offset0:90 offset1:123
	s_waitcnt lgkmcnt(0)
	v_mul_f32_e32 v19, v24, v21
	v_mul_f32_e32 v5, v25, v20
	v_cvt_pk_bf16_f32 v19, v5, v19
	ds_read2_b32 v[20:21], v52 offset0:156 offset1:189
	s_waitcnt lgkmcnt(0)
	v_mul_f32_e32 v5, v27, v20
	v_mul_f32_e32 v20, v26, v21
	v_cvt_pk_bf16_f32 v20, v5, v20
	ds_read2_b32 v[24:25], v52 offset0:222 offset1:255
	v_add_u32_e32 v5, v58, v55
	v_ashrrev_i32_e32 v26, 31, v5
	s_waitcnt lgkmcnt(0)
	v_mul_f32_e32 v21, v29, v24
	v_mul_f32_e32 v22, v28, v25
	v_mad_u64_u32 v[24:25], s[0:1], v5, s3, 0
	v_cvt_pk_bf16_f32 v21, v21, v22
	v_mov_b32_e32 v22, v25
	v_mad_u64_u32 v[26:27], s[0:1], v26, s3, v[22:23]
	v_mov_b32_e32 v25, v26
	v_lshl_add_u64 v[24:25], v[24:25], 1, v[34:35]
	global_store_dwordx4 v[24:25], v[18:21], off
	s_andn2_b64 exec, exec, s[8:9]
	s_cbranch_execz .LBB0_483

; __device__ __forceinline__ void phase_prep(const Args& a, float* ldsf) {
;     ...
;     convert_weights(a, ldsf, CONV_PREP_MASK, (int)blockIdx.x, (int)gridDim.x);
;     {
;         const int gt = blockIdx.x * NTHREADS + tid, NGT = gridDim.x * NTHREADS;
;         const int per = (SSD_IN_PAD - SSD_IN_N) * 1024 * 2 / 16;
;         for (int i = gt; i < 2 * per; i += NGT) { const int j = i / per, r = i % per; ((uint4*)(ws + WS_SSDIN + j * SZ_SSDIN1 + (size_t)SSD_IN_N * 1024 * 2))[r] = make_uint4(0, 0, 0, 0); }
.LBB0_542:
	s_bitcmp1_b32 s100, 16
	s_cbranch_scc1 .Lcv_tail_ret
	v_readlane_b32 s0, v254, 3
	s_nop 1
	v_add_u32_e32 v4, s0, v13
	s_mov_b32 s0, 0xe000
	v_cmp_gt_i32_e32 vcc, s0, v4
	s_and_saveexec_b64 s[0:1], vcc
	s_cbranch_execz .LBB0_545
	s_mov_b64 s[4:5], 0
	v_mov_b32_e32 v1, v4

; __global__ void __launch_bounds__(NTHREADS, 2) mk_fwd(Args a) {
;     extern __shared__ __attribute__((aligned(16))) unsigned char lds[];
	.amdhsa_kernel _Z6mk_fwd4Args
		.amdhsa_group_segment_fixed_size 0
		.amdhsa_private_segment_fixed_size 0
		.amdhsa_kernarg_size 440
		.amdhsa_user_sgpr_count 2
		.amdhsa_user_sgpr_dispatch_ptr 0
		.amdhsa_user_sgpr_queue_ptr 0
		.amdhsa_user_sgpr_kernarg_segment_ptr 1
		.amdhsa_user_sgpr_dispatch_id 0
		.amdhsa_user_sgpr_kernarg_preload_length 0
		.amdhsa_user_sgpr_kernarg_preload_offset 0
		.amdhsa_user_sgpr_private_segment_size 0
		.amdhsa_uses_dynamic_stack 0
		.amdhsa_enable_private_segment 0
		.amdhsa_system_sgpr_workgroup_id_x 1
		.amdhsa_system_sgpr_workgroup_id_y 0
		.amdhsa_system_sgpr_workgroup_id_z 0
		.amdhsa_system_sgpr_workgroup_info 0
		.amdhsa_system_vgpr_workitem_id 0
		.amdhsa_next_free_vgpr 256
		.amdhsa_next_free_sgpr 102
		.amdhsa_accum_offset 256
		.amdhsa_reserve_vcc 1
		.amdhsa_float_round_mode_32 0
		.amdhsa_float_round_mode_16_64 0
		.amdhsa_float_denorm_mode_32 3
		.amdhsa_float_denorm_mode_16_64 3
		.amdhsa_dx10_clamp 1
		.amdhsa_ieee_mode 1
		.amdhsa_fp16_overflow 0
		.amdhsa_tg_split 0
		.amdhsa_exception_fp_ieee_invalid_op 0
		.amdhsa_exception_fp_denorm_src 0
		.amdhsa_exception_fp_ieee_div_zero 0
		.amdhsa_exception_fp_ieee_overflow 0
		.amdhsa_exception_fp_ieee_underflow 0
		.amdhsa_exception_fp_ieee_inexact 0
		.amdhsa_exception_int_div_zero 0
	.end_amdhsa_kernel

; __global__ void __launch_bounds__(NTHREADS, 2) mk_fwd(Args a) {
amdhsa.kernels:
  - .agpr_count:     0
    .args:
      - .offset:         0
        .size:           184
        .value_kind:     by_value
      - .offset:         184
        .size:           4
        .value_kind:     hidden_block_count_x
      - .offset:         188
        .size:           4
        .value_kind:     hidden_block_count_y
      - .offset:         192
        .size:           4
        .value_kind:     hidden_block_count_z
      - .offset:         196
        .size:           2
        .value_kind:     hidden_group_size_x
      - .offset:         198
        .size:           2
        .value_kind:     hidden_group_size_y
      - .offset:         200
        .size:           2
        .value_kind:     hidden_group_size_z
      - .offset:         202
        .size:           2
        .value_kind:     hidden_remainder_x
      - .offset:         204
        .size:           2
        .value_kind:     hidden_remainder_y
      - .offset:         206
        .size:           2
        .value_kind:     hidden_remainder_z
      - .offset:         224
        .size:           8
        .value_kind:     hidden_global_offset_x
      - .offset:         232
        .size:           8
        .value_kind:     hidden_global_offset_y
      - .offset:         240
        .size:           8
        .value_kind:     hidden_global_offset_z
      - .offset:         248
        .size:           2
        .value_kind:     hidden_grid_dims
      - .offset:         304
        .size:           4
        .value_kind:     hidden_dynamic_lds_size
    .group_segment_fixed_size: 0
    .kernarg_segment_align: 8
    .kernarg_segment_size: 440
    .language:       OpenCL C
    .language_version:
      - 2
      - 0
    .max_flat_workgroup_size: 512
    .name:           _Z6mk_fwd4Args
    .private_segment_fixed_size: 0
    .sgpr_count:     108
    .sgpr_spill_count: 258
    .symbol:         _Z6mk_fwd4Args.kd
    .uniform_work_group_size: 1
    .uses_dynamic_stack: false
    .vgpr_count:     256
    .vgpr_spill_count: 0
    .wavefront_size: 64
